# attention epilogue: 16 dwordx2 stores per lane replaced by 8 dwordx4 stores after a permlane32_swap exchange between wave halves
# baseline (speedup 1.0000x reference)
; #define LAS __attribute__((address_space(3)))
; __device__ __forceinline__ int crow(int r, int hi) { return (r & 3) + 8 * (r >> 2) + 4 * hi; }
; __device__ __forceinline__ void attn_item(CP& P, int L, int sq, int hh, int qt, float lam, float lam_init, LAS unsigned char* lds) {
;     ...
;     LAS float* O2 = (LAS float*)lds;
;     if (map == 1) {
; #pragma unroll
;         for (int c = 0; c < 4; ++c)
; #pragma unroll
;             for (int i = 0; i < 16; ++i) O2[(wq * 32 + r) * A_O2P + 32 * c + crow(i, hi)] = o[c][i] * inv;
;     }
;     __syncthreads();
;     if (map == 0) {
;         float ss = 0.f;
; #pragma unroll
;         for (int c = 0; c < 4; ++c)
; #pragma unroll
;             for (int i = 0; i < 16; ++i) { const float v = o[c][i] * inv - lam * O2[(wq * 32 + r) * A_O2P + 32 * c + crow(i, hi)]; o[c][i] = v; ss += v * v; }
;         ss += __shfl_xor(ss, 32);
;         const float rstd = rsqrtf(ss * (1.f / 128.f) + EPS) * (1.f - lam_init);
;         const float* sg = P.in[I_SUBLN] + L * 128;
;         bf16_t* op = mix + (size_t)(sstart + qpos) * DM + 1280 + hh * 128;
; #pragma unroll
;         for (int c = 0; c < 4; ++c)
; #pragma unroll
;             for (int gq = 0; gq < 4; ++gq) { const int dv = 32 * c + 8 * gq + 4 * hi; const f32x4 gg = *(const f32x4*)(sg + dv);
.LBB0_78:
	s_cmpk_gt_u32 s7, 0xff
	s_waitcnt lgkmcnt(0)
	s_barrier
	s_cbranch_scc1 .LBB0_80
	v_or_b32_e32 v66, s8, v128
	s_movk_i32 s0, 0x210
	v_mul_lo_u32 v66, v66, s0
	v_add3_u32 v128, 0, v66, v65
	ds_read_b128 v[66:69], v128 offset:480
	ds_read_b128 v[70:73], v128 offset:448
	ds_read_b128 v[74:77], v128
	ds_read_b128 v[82:85], v128 offset:32
	s_load_dwordx2 s[0:1], s[64:65], 0xa0
	s_waitcnt lgkmcnt(0)
	v_pk_mul_f32 v[66:67], v[66:67], v[112:113]
	v_pk_mul_f32 v[68:69], v[68:69], v[112:113]
	v_pk_fma_f32 v[66:67], v[28:29], v[64:65], v[66:67] op_sel_hi:[1,0,1] neg_lo:[0,0,1] neg_hi:[0,0,1]
	v_pk_fma_f32 v[28:29], v[30:31], v[64:65], v[68:69] op_sel_hi:[1,0,1] neg_lo:[0,0,1] neg_hi:[0,0,1]
	v_pk_mul_f32 v[30:31], v[76:77], v[112:113]
	v_readlane_b32 s4, v254, 2
	v_pk_fma_f32 v[76:77], v[2:3], v[64:65], v[30:31] op_sel_hi:[1,0,1] neg_lo:[0,0,1] neg_hi:[0,0,1]
	v_pk_mul_f32 v[2:3], v[74:75], v[112:113]
	v_readlane_b32 s5, v254, 3
	v_pk_fma_f32 v[74:75], v[0:1], v[64:65], v[2:3] op_sel_hi:[1,0,1] neg_lo:[0,0,1] neg_hi:[0,0,1]
	v_pk_mul_f32 v[0:1], v[84:85], v[112:113]
	s_add_u32 s0, s0, s4
	v_pk_fma_f32 v[84:85], v[6:7], v[64:65], v[0:1] op_sel_hi:[1,0,1] neg_lo:[0,0,1] neg_hi:[0,0,1]
	ds_read_b128 v[0:3], v128 offset:64
	v_pk_mul_f32 v[6:7], v[82:83], v[112:113]
	s_addc_u32 s1, s1, s5
	v_pk_fma_f32 v[82:83], v[4:5], v[64:65], v[6:7] op_sel_hi:[1,0,1] neg_lo:[0,0,1] neg_hi:[0,0,1]
	ds_read_b128 v[4:7], v128 offset:96
	s_waitcnt lgkmcnt(1)
	v_pk_mul_f32 v[0:1], v[0:1], v[112:113]
	v_pk_mul_f32 v[2:3], v[2:3], v[112:113]
	v_pk_fma_f32 v[100:101], v[8:9], v[64:65], v[0:1] op_sel_hi:[1,0,1] neg_lo:[0,0,1] neg_hi:[0,0,1]
	v_pk_fma_f32 v[96:97], v[10:11], v[64:65], v[2:3] op_sel_hi:[1,0,1] neg_lo:[0,0,1] neg_hi:[0,0,1]
	s_waitcnt lgkmcnt(0)
	v_pk_mul_f32 v[0:1], v[6:7], v[112:113]
	v_pk_mul_f32 v[4:5], v[4:5], v[112:113]
	v_pk_fma_f32 v[104:105], v[14:15], v[64:65], v[0:1] op_sel_hi:[1,0,1] neg_lo:[0,0,1] neg_hi:[0,0,1]
	ds_read_b128 v[0:3], v128 offset:128
	v_pk_fma_f32 v[108:109], v[12:13], v[64:65], v[4:5] op_sel_hi:[1,0,1] neg_lo:[0,0,1] neg_hi:[0,0,1]
	ds_read_b128 v[4:7], v128 offset:160
	v_pk_mul_f32 v[90:91], v[74:75], v[74:75]
	global_load_dwordx4 v[78:81], v65, s[0:1]
	global_load_dwordx4 v[146:149], v65, s[0:1] offset:32
	global_load_dwordx4 v[150:153], v65, s[0:1] offset:64
	global_load_dwordx4 v[154:157], v65, s[0:1] offset:96
	global_load_dwordx4 v[158:161], v65, s[0:1] offset:128
	global_load_dwordx4 v[162:165], v65, s[0:1] offset:160
	global_load_dwordx4 v[166:169], v65, s[0:1] offset:192
	global_load_dwordx4 v[170:173], v65, s[0:1] offset:224
	global_load_dwordx4 v[174:177], v65, s[0:1] offset:256
	global_load_dwordx4 v[178:181], v65, s[0:1] offset:288
	global_load_dwordx4 v[182:185], v65, s[0:1] offset:320
	global_load_dwordx4 v[186:189], v65, s[0:1] offset:352
	global_load_dwordx4 v[200:203], v65, s[0:1] offset:384
	global_load_dwordx4 v[208:211], v65, s[0:1] offset:416
	global_load_dwordx4 v[212:215], v65, s[0:1] offset:448
	global_load_dwordx4 v[216:219], v65, s[0:1] offset:480
	s_waitcnt lgkmcnt(1)
	v_pk_mul_f32 v[0:1], v[0:1], v[112:113]
	v_pk_mul_f32 v[2:3], v[2:3], v[112:113]
	v_pk_fma_f32 v[48:49], v[48:49], v[64:65], v[0:1] op_sel_hi:[1,0,1] neg_lo:[0,0,1] neg_hi:[0,0,1]
	s_waitcnt lgkmcnt(0)
	v_pk_mul_f32 v[0:1], v[6:7], v[112:113]
	v_pk_fma_f32 v[50:51], v[50:51], v[64:65], v[2:3] op_sel_hi:[1,0,1] neg_lo:[0,0,1] neg_hi:[0,0,1]
	v_pk_fma_f32 v[54:55], v[54:55], v[64:65], v[0:1] op_sel_hi:[1,0,1] neg_lo:[0,0,1] neg_hi:[0,0,1]
	ds_read_b128 v[0:3], v128 offset:192
	v_pk_mul_f32 v[4:5], v[4:5], v[112:113]
	v_pk_mul_f32 v[88:89], v[76:77], v[76:77]
	v_pk_fma_f32 v[52:53], v[52:53], v[64:65], v[4:5] op_sel_hi:[1,0,1] neg_lo:[0,0,1] neg_hi:[0,0,1]
	ds_read_b128 v[4:7], v128 offset:224
	s_waitcnt lgkmcnt(1)
	v_pk_mul_f32 v[0:1], v[0:1], v[112:113]
	v_pk_mul_f32 v[2:3], v[2:3], v[112:113]
	v_pk_fma_f32 v[56:57], v[56:57], v[64:65], v[0:1] op_sel_hi:[1,0,1] neg_lo:[0,0,1] neg_hi:[0,0,1]
	v_pk_fma_f32 v[58:59], v[58:59], v[64:65], v[2:3] op_sel_hi:[1,0,1] neg_lo:[0,0,1] neg_hi:[0,0,1]
	s_waitcnt lgkmcnt(0)
	v_pk_mul_f32 v[0:1], v[6:7], v[112:113]
	v_pk_mul_f32 v[4:5], v[4:5], v[112:113]
	v_pk_fma_f32 v[62:63], v[62:63], v[64:65], v[0:1] op_sel_hi:[1,0,1] neg_lo:[0,0,1] neg_hi:[0,0,1]
	ds_read_b128 v[0:3], v128 offset:256
	v_pk_fma_f32 v[60:61], v[60:61], v[64:65], v[4:5] op_sel_hi:[1,0,1] neg_lo:[0,0,1] neg_hi:[0,0,1]
	ds_read_b128 v[4:7], v128 offset:288
	v_pk_mul_f32 v[94:95], v[82:83], v[82:83]
	v_pk_mul_f32 v[92:93], v[84:85], v[84:85]
	s_waitcnt lgkmcnt(1)
	v_pk_mul_f32 v[0:1], v[0:1], v[112:113]
	v_pk_mul_f32 v[2:3], v[2:3], v[112:113]
	v_pk_fma_f32 v[140:141], v[32:33], v[64:65], v[0:1] op_sel_hi:[1,0,1] neg_lo:[0,0,1] neg_hi:[0,0,1]
	s_waitcnt lgkmcnt(0)
	v_pk_mul_f32 v[0:1], v[6:7], v[112:113]
	v_pk_fma_f32 v[136:137], v[34:35], v[64:65], v[2:3] op_sel_hi:[1,0,1] neg_lo:[0,0,1] neg_hi:[0,0,1]
	v_pk_fma_f32 v[32:33], v[38:39], v[64:65], v[0:1] op_sel_hi:[1,0,1] neg_lo:[0,0,1] neg_hi:[0,0,1]
	ds_read_b128 v[0:3], v128 offset:320
	v_pk_mul_f32 v[4:5], v[4:5], v[112:113]
	v_pk_mul_f32 v[102:103], v[100:101], v[100:101]
	v_pk_fma_f32 v[36:37], v[36:37], v[64:65], v[4:5] op_sel_hi:[1,0,1] neg_lo:[0,0,1] neg_hi:[0,0,1]
	ds_read_b128 v[4:7], v128 offset:352
	s_waitcnt lgkmcnt(1)
	v_pk_mul_f32 v[0:1], v[0:1], v[112:113]
	v_pk_mul_f32 v[2:3], v[2:3], v[112:113]
	v_pk_fma_f32 v[34:35], v[40:41], v[64:65], v[0:1] op_sel_hi:[1,0,1] neg_lo:[0,0,1] neg_hi:[0,0,1]
	v_pk_fma_f32 v[30:31], v[42:43], v[64:65], v[2:3] op_sel_hi:[1,0,1] neg_lo:[0,0,1] neg_hi:[0,0,1]
	s_waitcnt lgkmcnt(0)
; __device__ __forceinline__ int crow(int r, int hi) { return (r & 3) + 8 * (r >> 2) + 4 * hi; }
; __device__ __forceinline__ void attn_item(CP& P, int L, int sq, int hh, int qt, float lam, float lam_init, LAS unsigned char* lds) {
;     ...
;         float ss = 0.f;
; #pragma unroll
;         for (int c = 0; c < 4; ++c)
; #pragma unroll
;             for (int i = 0; i < 16; ++i) { const float v = o[c][i] * inv - lam * O2[(wq * 32 + r) * A_O2P + 32 * c + crow(i, hi)]; o[c][i] = v; ss += v * v; }
;         ss += __shfl_xor(ss, 32);
;         const float rstd = rsqrtf(ss * (1.f / 128.f) + EPS) * (1.f - lam_init);
;         const float* sg = P.in[I_SUBLN] + L * 128;
;         bf16_t* op = mix + (size_t)(sstart + qpos) * DM + 1280 + hh * 128;
	v_pk_mul_f32 v[0:1], v[6:7], v[112:113]
	v_pk_mul_f32 v[4:5], v[4:5], v[112:113]
	v_pk_fma_f32 v[10:11], v[46:47], v[64:65], v[0:1] op_sel_hi:[1,0,1] neg_lo:[0,0,1] neg_hi:[0,0,1]
	ds_read_b128 v[0:3], v128 offset:384
	v_pk_fma_f32 v[14:15], v[44:45], v[64:65], v[4:5] op_sel_hi:[1,0,1] neg_lo:[0,0,1] neg_hi:[0,0,1]
	ds_read_b128 v[4:7], v128 offset:416
	v_pk_mul_f32 v[98:99], v[96:97], v[96:97]
	v_pk_mul_f32 v[110:111], v[108:109], v[108:109]
	s_waitcnt lgkmcnt(1)
	v_pk_mul_f32 v[0:1], v[0:1], v[112:113]
	v_pk_mul_f32 v[2:3], v[2:3], v[112:113]
	v_pk_fma_f32 v[12:13], v[16:17], v[64:65], v[0:1] op_sel_hi:[1,0,1] neg_lo:[0,0,1] neg_hi:[0,0,1]
	s_waitcnt lgkmcnt(0)
	v_pk_mul_f32 v[0:1], v[6:7], v[112:113]
	v_pk_fma_f32 v[8:9], v[18:19], v[64:65], v[2:3] op_sel_hi:[1,0,1] neg_lo:[0,0,1] neg_hi:[0,0,1]
	v_pk_fma_f32 v[2:3], v[22:23], v[64:65], v[0:1] op_sel_hi:[1,0,1] neg_lo:[0,0,1] neg_hi:[0,0,1]
	v_pk_mul_f32 v[0:1], v[4:5], v[112:113]
	v_pk_mul_f32 v[4:5], v[70:71], v[112:113]
	v_pk_fma_f32 v[6:7], v[20:21], v[64:65], v[0:1] op_sel_hi:[1,0,1] neg_lo:[0,0,1] neg_hi:[0,0,1]
	v_pk_mul_f32 v[0:1], v[72:73], v[112:113]
	v_pk_fma_f32 v[4:5], v[24:25], v[64:65], v[4:5] op_sel_hi:[1,0,1] neg_lo:[0,0,1] neg_hi:[0,0,1]
	v_pk_fma_f32 v[0:1], v[26:27], v[64:65], v[0:1] op_sel_hi:[1,0,1] neg_lo:[0,0,1] neg_hi:[0,0,1]
	v_add_f32_e32 v64, v90, v91
	v_add_f32_e32 v64, v64, v88
	v_add_f32_e32 v64, v64, v89
	v_add_f32_e32 v64, v64, v94
	v_add_f32_e32 v64, v64, v95
	v_add_f32_e32 v64, v64, v92
	v_add_f32_e32 v64, v64, v93
	v_add_f32_e32 v64, v64, v102
	v_add_f32_e32 v64, v64, v103
	v_add_f32_e32 v64, v64, v98
	v_add_f32_e32 v64, v64, v99
	v_add_f32_e32 v64, v64, v110
	v_pk_mul_f32 v[106:107], v[104:105], v[104:105]
	v_add_f32_e32 v64, v64, v111
	v_add_f32_e32 v64, v64, v106
	v_pk_mul_f32 v[118:119], v[48:49], v[48:49]
	v_add_f32_e32 v64, v64, v107
	v_add_f32_e32 v64, v64, v118
	v_pk_mul_f32 v[116:117], v[50:51], v[50:51]
	v_add_f32_e32 v64, v64, v119
	v_add_f32_e32 v64, v64, v116
	v_pk_mul_f32 v[122:123], v[52:53], v[52:53]
	v_add_f32_e32 v64, v64, v117
	v_add_f32_e32 v64, v64, v122
	v_pk_mul_f32 v[120:121], v[54:55], v[54:55]
	v_add_f32_e32 v64, v64, v123
	v_add_f32_e32 v64, v64, v120
	v_pk_mul_f32 v[130:131], v[56:57], v[56:57]
	v_add_f32_e32 v64, v64, v121
	v_add_f32_e32 v64, v64, v130
	v_pk_mul_f32 v[124:125], v[58:59], v[58:59]
	v_add_f32_e32 v64, v64, v131
	v_add_f32_e32 v64, v64, v124
	v_pk_mul_f32 v[134:135], v[60:61], v[60:61]
	v_add_f32_e32 v64, v64, v125
	v_add_f32_e32 v64, v64, v134
	v_pk_mul_f32 v[132:133], v[62:63], v[62:63]
	v_add_f32_e32 v64, v64, v135
	v_add_f32_e32 v64, v64, v132
	v_pk_mul_f32 v[142:143], v[140:141], v[140:141]
	v_add_f32_e32 v64, v64, v133
	v_add_f32_e32 v64, v64, v142
	v_pk_mul_f32 v[138:139], v[136:137], v[136:137]
	v_add_f32_e32 v64, v64, v143
	v_add_f32_e32 v64, v64, v138
	v_pk_mul_f32 v[144:145], v[36:37], v[36:37]
	v_add_f32_e32 v64, v64, v139
	v_add_f32_e32 v64, v64, v144
	v_pk_mul_f32 v[38:39], v[32:33], v[32:33]
	v_add_f32_e32 v64, v64, v145
	v_add_f32_e32 v38, v64, v38
	v_pk_mul_f32 v[40:41], v[34:35], v[34:35]
	v_add_f32_e32 v38, v38, v39
	v_add_f32_e32 v38, v38, v40
	v_pk_mul_f32 v[42:43], v[30:31], v[30:31]
	v_add_f32_e32 v38, v38, v41
	v_add_f32_e32 v38, v38, v42
	v_pk_mul_f32 v[44:45], v[14:15], v[14:15]
	v_add_f32_e32 v38, v38, v43
	v_add_f32_e32 v38, v38, v44
	v_pk_mul_f32 v[46:47], v[10:11], v[10:11]
	v_add_f32_e32 v38, v38, v45
	v_add_f32_e32 v38, v38, v46
	v_pk_mul_f32 v[16:17], v[12:13], v[12:13]
	v_add_f32_e32 v38, v38, v47
	v_add_f32_e32 v16, v38, v16
	v_pk_mul_f32 v[18:19], v[8:9], v[8:9]
	v_add_f32_e32 v16, v16, v17
	v_add_f32_e32 v16, v16, v18
	v_pk_mul_f32 v[20:21], v[6:7], v[6:7]
	v_add_f32_e32 v16, v16, v19
	v_add_f32_e32 v16, v16, v20
	v_pk_mul_f32 v[22:23], v[2:3], v[2:3]
	v_add_f32_e32 v16, v16, v21
	v_add_f32_e32 v16, v16, v22
	v_pk_mul_f32 v[24:25], v[4:5], v[4:5]
	v_add_f32_e32 v16, v16, v23
	v_add_f32_e32 v16, v16, v24
	v_pk_mul_f32 v[26:27], v[0:1], v[0:1]
	v_add_f32_e32 v16, v16, v25
	v_add_f32_e32 v16, v16, v26
	v_pk_mul_f32 v[68:69], v[66:67], v[66:67]
	v_add_f32_e32 v16, v16, v27
	v_add_f32_e32 v16, v16, v68
	v_pk_mul_f32 v[86:87], v[28:29], v[28:29]
	v_add_f32_e32 v16, v16, v69
	v_add_f32_e32 v16, v16, v86
	v_add_f32_e32 v18, v16, v87
	ds_bpermute_b32 v19, v129, v18
	v_lshlrev_b64 v[16:17], 12, v[114:115]
	v_lshl_add_u64 v[16:17], s[26:27], 0, v[16:17]
	s_lshl_b32 s2, s2, 1
	v_lshl_add_u64 v[16:17], v[16:17], 0, s[2:3]
	s_waitcnt lgkmcnt(0)
	v_add_f32_e32 v18, v18, v19
	v_fmamk_f32 v18, v18, 0x3c000000, v194
	v_mul_f32_e32 v19, 0x4b800000, v18
	v_cmp_gt_f32_e32 vcc, s72, v18
	v_lshlrev_b32_e32 v192, 2, v127
	v_lshl_add_u64 v[20:21], v[16:17], 0, v[192:193]
	v_cndmask_b32_e32 v18, v18, v19, vcc
	v_rsq_f32_e32 v18, v18
	s_mov_b64 s[4:5], 0x2c600a00
	v_mul_f32_e32 v16, 0x45800000, v18
	v_cndmask_b32_e32 v16, v18, v16, vcc
	v_mul_f32_e32 v22, v126, v16
	v_lshl_add_u64 v[20:21], v[20:21], 0, s[4:5]
	s_waitcnt vmcnt(0)
; __device__ __forceinline__ unsigned cvtpk(float lo, float hi) { f32x2 v = {lo, hi}; bf16x2_t b = __builtin_convertvector(v, bf16x2_t); return __builtin_bit_cast(unsigned, b); }
; __device__ __forceinline__ void attn_item(CP& P, int L, int sq, int hh, int qt, float lam, float lam_init, LAS unsigned char* lds) {
;     ...
; #pragma unroll
;         for (int c = 0; c < 4; ++c)
; #pragma unroll
;             for (int gq = 0; gq < 4; ++gq) { const int dv = 32 * c + 8 * gq + 4 * hi; const f32x4 gg = *(const f32x4*)(sg + dv);
;                 u32x2 w; w.x = cvtpk(o[c][4 * gq] * rstd * gg.x, o[c][4 * gq + 1] * rstd * gg.y); w.y = cvtpk(o[c][4 * gq + 2] * rstd * gg.z, o[c][4 * gq + 3] * rstd * gg.w);
;                 *(u32x2*)(op + dv) = w; }
	v_pk_mul_f32 v[24:25], v[82:83], v[22:23] op_sel_hi:[1,0]
	v_pk_mul_f32 v[26:27], v[84:85], v[22:23] op_sel_hi:[1,0]
	v_pk_mul_f32 v[16:17], v[74:75], v[22:23] op_sel_hi:[1,0]
	v_pk_mul_f32 v[18:19], v[76:77], v[22:23] op_sel_hi:[1,0]
	v_pk_mul_f32 v[24:25], v[24:25], v[146:147]
	v_pk_mul_f32 v[26:27], v[26:27], v[148:149]
	v_pk_mul_f32 v[16:17], v[16:17], v[78:79]
	v_pk_mul_f32 v[18:19], v[18:19], v[80:81]
	v_cvt_pk_bf16_f32 v16, v16, v17
	v_cvt_pk_bf16_f32 v17, v18, v19
	v_cvt_pk_bf16_f32 v18, v24, v25
	v_cvt_pk_bf16_f32 v19, v26, v27
	s_nop 1
	v_permlane32_swap_b32_e32 v16, v18
	v_permlane32_swap_b32_e32 v17, v19
	global_store_dwordx4 v[20:21], v[16:19], off
	v_pk_mul_f32 v[24:25], v[108:109], v[22:23] op_sel_hi:[1,0]
	v_pk_mul_f32 v[26:27], v[104:105], v[22:23] op_sel_hi:[1,0]
	v_pk_mul_f32 v[16:17], v[100:101], v[22:23] op_sel_hi:[1,0]
	v_pk_mul_f32 v[18:19], v[96:97], v[22:23] op_sel_hi:[1,0]
	v_pk_mul_f32 v[24:25], v[24:25], v[154:155]
	v_pk_mul_f32 v[26:27], v[26:27], v[156:157]
	v_pk_mul_f32 v[16:17], v[16:17], v[150:151]
	v_pk_mul_f32 v[18:19], v[18:19], v[152:153]
	v_cvt_pk_bf16_f32 v16, v16, v17
	v_cvt_pk_bf16_f32 v17, v18, v19
	v_cvt_pk_bf16_f32 v18, v24, v25
	v_cvt_pk_bf16_f32 v19, v26, v27
	s_nop 1
	v_permlane32_swap_b32_e32 v16, v18
	v_permlane32_swap_b32_e32 v17, v19
	global_store_dwordx4 v[20:21], v[16:19], off offset:32
	v_pk_mul_f32 v[24:25], v[52:53], v[22:23] op_sel_hi:[1,0]
	v_pk_mul_f32 v[26:27], v[54:55], v[22:23] op_sel_hi:[1,0]
	v_pk_mul_f32 v[16:17], v[48:49], v[22:23] op_sel_hi:[1,0]
	v_pk_mul_f32 v[18:19], v[50:51], v[22:23] op_sel_hi:[1,0]
	v_pk_mul_f32 v[24:25], v[24:25], v[162:163]
	v_pk_mul_f32 v[26:27], v[26:27], v[164:165]
	v_pk_mul_f32 v[16:17], v[16:17], v[158:159]
	v_pk_mul_f32 v[18:19], v[18:19], v[160:161]
	v_cvt_pk_bf16_f32 v16, v16, v17
	v_cvt_pk_bf16_f32 v17, v18, v19
	v_cvt_pk_bf16_f32 v18, v24, v25
	v_cvt_pk_bf16_f32 v19, v26, v27
	s_nop 1
	v_permlane32_swap_b32_e32 v16, v18
	v_permlane32_swap_b32_e32 v17, v19
	global_store_dwordx4 v[20:21], v[16:19], off offset:64
	v_pk_mul_f32 v[24:25], v[60:61], v[22:23] op_sel_hi:[1,0]
	v_pk_mul_f32 v[26:27], v[62:63], v[22:23] op_sel_hi:[1,0]
	v_pk_mul_f32 v[16:17], v[56:57], v[22:23] op_sel_hi:[1,0]
	v_pk_mul_f32 v[18:19], v[58:59], v[22:23] op_sel_hi:[1,0]
	v_pk_mul_f32 v[24:25], v[24:25], v[170:171]
	v_pk_mul_f32 v[26:27], v[26:27], v[172:173]
	v_pk_mul_f32 v[16:17], v[16:17], v[166:167]
	v_pk_mul_f32 v[18:19], v[18:19], v[168:169]
	v_cvt_pk_bf16_f32 v16, v16, v17
	v_cvt_pk_bf16_f32 v17, v18, v19
	v_cvt_pk_bf16_f32 v18, v24, v25
	v_cvt_pk_bf16_f32 v19, v26, v27
	s_nop 1
	v_permlane32_swap_b32_e32 v16, v18
	v_permlane32_swap_b32_e32 v17, v19
	global_store_dwordx4 v[20:21], v[16:19], off offset:96
	v_pk_mul_f32 v[24:25], v[36:37], v[22:23] op_sel_hi:[1,0]
	v_pk_mul_f32 v[26:27], v[32:33], v[22:23] op_sel_hi:[1,0]
	v_pk_mul_f32 v[16:17], v[140:141], v[22:23] op_sel_hi:[1,0]
	v_pk_mul_f32 v[18:19], v[136:137], v[22:23] op_sel_hi:[1,0]
	v_pk_mul_f32 v[24:25], v[24:25], v[178:179]
	v_pk_mul_f32 v[26:27], v[26:27], v[180:181]
	v_pk_mul_f32 v[16:17], v[16:17], v[174:175]
	v_pk_mul_f32 v[18:19], v[18:19], v[176:177]
	v_cvt_pk_bf16_f32 v16, v16, v17
	v_cvt_pk_bf16_f32 v17, v18, v19
	v_cvt_pk_bf16_f32 v18, v24, v25
	v_cvt_pk_bf16_f32 v19, v26, v27
	s_nop 1
	v_permlane32_swap_b32_e32 v16, v18
	v_permlane32_swap_b32_e32 v17, v19
	global_store_dwordx4 v[20:21], v[16:19], off offset:128
	v_pk_mul_f32 v[24:25], v[14:15], v[22:23] op_sel_hi:[1,0]
	v_pk_mul_f32 v[26:27], v[10:11], v[22:23] op_sel_hi:[1,0]
	v_pk_mul_f32 v[16:17], v[34:35], v[22:23] op_sel_hi:[1,0]
	v_pk_mul_f32 v[18:19], v[30:31], v[22:23] op_sel_hi:[1,0]
	v_pk_mul_f32 v[24:25], v[24:25], v[186:187]
	v_pk_mul_f32 v[26:27], v[26:27], v[188:189]
	v_pk_mul_f32 v[16:17], v[16:17], v[182:183]
	v_pk_mul_f32 v[18:19], v[18:19], v[184:185]
	v_cvt_pk_bf16_f32 v16, v16, v17
	v_cvt_pk_bf16_f32 v17, v18, v19
	v_cvt_pk_bf16_f32 v18, v24, v25
	v_cvt_pk_bf16_f32 v19, v26, v27
	s_nop 1
	v_permlane32_swap_b32_e32 v16, v18
	v_permlane32_swap_b32_e32 v17, v19
	global_store_dwordx4 v[20:21], v[16:19], off offset:160
	v_pk_mul_f32 v[24:25], v[6:7], v[22:23] op_sel_hi:[1,0]
	v_pk_mul_f32 v[26:27], v[2:3], v[22:23] op_sel_hi:[1,0]
	v_pk_mul_f32 v[16:17], v[12:13], v[22:23] op_sel_hi:[1,0]
	v_pk_mul_f32 v[18:19], v[8:9], v[22:23] op_sel_hi:[1,0]
	v_pk_mul_f32 v[24:25], v[24:25], v[208:209]
	v_pk_mul_f32 v[26:27], v[26:27], v[210:211]
	v_pk_mul_f32 v[16:17], v[16:17], v[200:201]
	v_pk_mul_f32 v[18:19], v[18:19], v[202:203]
	v_cvt_pk_bf16_f32 v16, v16, v17
	v_cvt_pk_bf16_f32 v17, v18, v19
	v_cvt_pk_bf16_f32 v18, v24, v25
	v_cvt_pk_bf16_f32 v19, v26, v27
	s_nop 1
	v_permlane32_swap_b32_e32 v16, v18
	v_permlane32_swap_b32_e32 v17, v19
	global_store_dwordx4 v[20:21], v[16:19], off offset:192
	v_pk_mul_f32 v[24:25], v[66:67], v[22:23] op_sel_hi:[1,0]
	v_pk_mul_f32 v[26:27], v[28:29], v[22:23] op_sel_hi:[1,0]
	v_pk_mul_f32 v[16:17], v[4:5], v[22:23] op_sel_hi:[1,0]
	v_pk_mul_f32 v[18:19], v[0:1], v[22:23] op_sel_hi:[1,0]
	v_pk_mul_f32 v[24:25], v[24:25], v[216:217]
	v_pk_mul_f32 v[26:27], v[26:27], v[218:219]
	v_pk_mul_f32 v[16:17], v[16:17], v[212:213]
	v_pk_mul_f32 v[18:19], v[18:19], v[214:215]
	v_cvt_pk_bf16_f32 v16, v16, v17
	v_cvt_pk_bf16_f32 v17, v18, v19
	v_cvt_pk_bf16_f32 v18, v24, v25
	v_cvt_pk_bf16_f32 v19, v26, v27
	s_nop 1
	v_permlane32_swap_b32_e32 v16, v18
	v_permlane32_swap_b32_e32 v17, v19
	global_store_dwordx4 v[20:21], v[16:19], off offset:224
